# RS4 + s_setprio 3 during scores+softmax (0 during P.V)
# speedup vs baseline: 1.0173x; 1.0002x over previous
.LBB0_538:
	s_add_i32 s2, s79, -1
	s_min_u32 s85, s2, s84
	s_lshl_b32 s4, s85, 6
	s_cmp_lt_u32 s85, 4
	s_cselect_b64 s[2:3], -1, 0
	s_add_i32 s88, s4, 0xffffff00
	s_and_b64 s[86:87], s[2:3], exec
	s_cselect_b32 s4, s4, s88
	s_cselect_b32 s88, s17, s73
	s_cselect_b32 s89, s16, s72
	s_lshl_b64 s[86:87], s[4:5], 7
	s_add_u32 s86, s89, s86
	s_addc_u32 s87, s88, s87
	s_lshl_b32 s88, s85, 1
	s_mov_b32 s89, s5
	s_lshl_b64 s[88:89], s[88:89], 2
	s_add_u32 s85, s18, s88
	s_addc_u32 s90, s19, s89
	s_add_u32 s88, s74, s88
	s_addc_u32 s89, s75, s89
	s_add_u32 s88, s88, 0xffffffe0
	s_addc_u32 s89, s89, -1
	s_and_b64 s[2:3], s[2:3], exec
	s_cselect_b32 s3, s90, s89
	s_cselect_b32 s2, s85, s88
	s_waitcnt vmcnt(0) lgkmcnt(0)
	s_barrier
	s_setprio 3
	s_waitcnt vmcnt(0)
	global_load_dwordx2 v[208:209], v201, s[2:3]
	s_cselect_b32 s85, s21, s77
	s_cselect_b32 s88, s20, s76
	s_lshl_b64 s[2:3], s[4:5], 9
	s_add_u32 s2, s88, s2
	ds_read_b128 v[180:183], v225
	ds_read_b128 v[184:187], v226
	s_addc_u32 s3, s85, s3
	s_cmp_lg_u32 0, -1
	s_cselect_b32 s4, 0, 0
	s_add_i32 s85, s4, s80
	s_add_i32 s4, s4, s81
	s_addk_i32 s85, 0x4000
	s_add_i32 s88, s4, 0x10000
	s_waitcnt lgkmcnt(1)
	v_mfma_i32_32x32x32_i8 v[148:163], v[180:183], v[164:167], v[132:147]
	ds_read_b128 v[180:183], v227
	s_waitcnt lgkmcnt(1)
	v_mfma_i32_32x32x32_i8 v[148:163], v[184:187], v[168:171], v[148:163]
	ds_read_b128 v[188:191], v228
	s_waitcnt lgkmcnt(1)
	v_mfma_i32_32x32x32_i8 v[148:163], v[180:183], v[172:175], v[148:163]
	ds_read_b64_tr_b16 v[184:185], v3 offset:32768
	ds_read_b64_tr_b16 v[186:187], v3 offset:36864
	s_waitcnt lgkmcnt(2)
	v_mfma_i32_32x32x32_i8 v[148:163], v[188:191], v[176:179], v[148:163]
	ds_read_b64_tr_b16 v[180:181], v3 offset:33280
	ds_read_b64_tr_b16 v[182:183], v3 offset:37376
	s_nop 9
	v_max3_f32 v188, v148, v149, v150
	v_max3_f32 v189, v151, v152, v153
	v_max3_f32 v190, v154, v155, v156
	v_max3_f32 v191, v157, v158, v159
	v_max3_f32 v192, v160, v161, v162
	v_max3_f32 v188, v188, v189, v190
	v_max3_f32 v191, v191, v192, v163
	v_max_f32_e32 v188, v188, v191
	v_add_f32_e32 v188, 0xcb400000, v188
	v_fma_f32 v189, v206, v188, -v237
	v_cmp_gt_f32_e32 vcc, v189, v220
	s_cbranch_vccnz .Lv2_rare_h1
.Lv2_back_h1:
	v_mul_f32_e32 v189, v221, v206
	v_fma_f32 v190, s100, v189, v255
	v_fma_f32 v148, v148, v189, -v190
	v_fma_f32 v149, v149, v189, -v190
	v_exp_f32_e32 v148, v148
	v_fma_f32 v150, v150, v189, -v190
	v_exp_f32_e32 v149, v149
	v_fma_f32 v151, v151, v189, -v190
	v_exp_f32_e32 v150, v150
	v_fma_f32 v152, v152, v189, -v190
	v_exp_f32_e32 v151, v151
	v_fma_f32 v153, v153, v189, -v190
	v_exp_f32_e32 v152, v152
	v_fma_f32 v154, v154, v189, -v190
	v_exp_f32_e32 v153, v153
	v_fma_f32 v155, v155, v189, -v190
	v_exp_f32_e32 v154, v154
	v_fma_f32 v156, v156, v189, -v190
	v_exp_f32_e32 v155, v155
	v_fma_f32 v157, v157, v189, -v190
	v_exp_f32_e32 v156, v156
	v_fma_f32 v158, v158, v189, -v190
	v_exp_f32_e32 v157, v157
	v_fma_f32 v159, v159, v189, -v190
	v_exp_f32_e32 v158, v158
	v_fma_f32 v160, v160, v189, -v190
	v_exp_f32_e32 v159, v159
	v_fma_f32 v161, v161, v189, -v190
	v_exp_f32_e32 v160, v160
	v_fma_f32 v162, v162, v189, -v190
	v_exp_f32_e32 v161, v161
	v_fma_f32 v163, v163, v189, -v190
	v_exp_f32_e32 v162, v162
	v_exp_f32_e32 v163, v163
	v_add_f32_e32 v188, v148, v149
	v_add_f32_e32 v189, v150, v151
	v_add_f32_e32 v190, v152, v153
	v_add_f32_e32 v191, v154, v155
	v_add_f32_e32 v192, v156, v157
	v_add_f32_e32 v193, v158, v159
	v_add_f32_e32 v194, v160, v161
	v_add_f32_e32 v195, v162, v163
	v_add_f32_e32 v188, v188, v189
	v_add_f32_e32 v190, v190, v191
	v_add_f32_e32 v192, v192, v193
	v_add_f32_e32 v194, v194, v195
	v_add_f32_e32 v188, v188, v190
	v_add_f32_e32 v192, v192, v194
	v_add_f32_e32 v188, v188, v192
	v_add_f32_e32 v224, v224, v188
	v_cvt_pk_bf16_f32 v155, v154, v155
	v_cvt_pk_bf16_f32 v154, v152, v153
	v_cvt_pk_bf16_f32 v152, v148, v149
	v_cvt_pk_bf16_f32 v153, v150, v151
	v_cvt_pk_bf16_f32 v148, v156, v157
	v_cvt_pk_bf16_f32 v149, v158, v159
	v_cvt_pk_bf16_f32 v150, v160, v161
	v_cvt_pk_bf16_f32 v151, v162, v163
	s_barrier
	s_setprio 0
	s_waitcnt lgkmcnt(2)
	v_mfma_f32_32x32x16_bf16 v[4:19], v[152:155], v[184:187], v[4:19]
	ds_read_b64_tr_b16 v[156:157], v3 offset:33792
	ds_read_b64_tr_b16 v[158:159], v3 offset:37888
	s_waitcnt lgkmcnt(2)
	v_mfma_f32_32x32x16_bf16 v[116:131], v[152:155], v[180:183], v[116:131]
	ds_read_b64_tr_b16 v[160:161], v3 offset:34304
	ds_read_b64_tr_b16 v[162:163], v3 offset:38400
	s_add_i32 m0, s80, 0x4000
	s_nop 0
	global_load_lds_dwordx4 v200, s[86:87]
	s_waitcnt lgkmcnt(2)
	v_mfma_f32_32x32x16_bf16 v[100:115], v[152:155], v[156:159], v[100:115]
	ds_read_b64_tr_b16 v[156:157], v3 offset:34816
	ds_read_b64_tr_b16 v[158:159], v3 offset:38912
	s_waitcnt lgkmcnt(2)
	v_mfma_f32_32x32x16_bf16 v[84:99], v[152:155], v[160:163], v[84:99]
	ds_read_b64_tr_b16 v[160:161], v3 offset:35328
	ds_read_b64_tr_b16 v[162:163], v3 offset:39424
	s_add_i32 m0, s81, 0x10000
	s_nop 0
	global_load_lds_dwordx4 v204, s[2:3]
	s_waitcnt lgkmcnt(2)
	v_mfma_f32_32x32x16_bf16 v[68:83], v[152:155], v[156:159], v[68:83]
	ds_read_b64_tr_b16 v[156:157], v3 offset:35840
	ds_read_b64_tr_b16 v[158:159], v3 offset:39936
	s_waitcnt lgkmcnt(2)
	v_mfma_f32_32x32x16_bf16 v[52:67], v[152:155], v[160:163], v[52:67]
	ds_read_b64_tr_b16 v[160:161], v3 offset:36352
	ds_read_b64_tr_b16 v[162:163], v3 offset:40448
	s_add_u32 s2, s2, 0x80
	s_addc_u32 s3, s3, 0
	s_add_i32 m0, s81, 0x10400
	s_nop 0
	global_load_lds_dwordx4 v204, s[2:3]
	s_waitcnt lgkmcnt(2)
	v_mfma_f32_32x32x16_bf16 v[36:51], v[152:155], v[156:159], v[36:51]
	ds_read_b64_tr_b16 v[156:157], v3 offset:40960
	ds_read_b64_tr_b16 v[158:159], v3 offset:45056
	s_waitcnt lgkmcnt(2)
	v_mfma_f32_32x32x16_bf16 v[20:35], v[152:155], v[160:163], v[20:35]
	ds_read_b64_tr_b16 v[152:153], v3 offset:41472
	ds_read_b64_tr_b16 v[154:155], v3 offset:45568
	s_add_u32 s2, s2, 0x80
	s_addc_u32 s3, s3, 0
	s_add_i32 m0, s81, 0x10800
	s_nop 0
	global_load_lds_dwordx4 v204, s[2:3]
	s_waitcnt lgkmcnt(2)
	v_mfma_f32_32x32x16_bf16 v[4:19], v[148:151], v[156:159], v[4:19]
	ds_read_b64_tr_b16 v[156:157], v3 offset:41984
	ds_read_b64_tr_b16 v[158:159], v3 offset:46080
	s_waitcnt lgkmcnt(2)
	v_mfma_f32_32x32x16_bf16 v[116:131], v[148:151], v[152:155], v[116:131]
	ds_read_b64_tr_b16 v[152:153], v3 offset:42496
	ds_read_b64_tr_b16 v[154:155], v3 offset:46592
	s_add_u32 s2, s2, 0x80
	s_addc_u32 s3, s3, 0
	s_add_i32 m0, s81, 0x10c00
	s_nop 0
	global_load_lds_dwordx4 v204, s[2:3]
	s_waitcnt lgkmcnt(2)
	v_mfma_f32_32x32x16_bf16 v[100:115], v[148:151], v[156:159], v[100:115]
	ds_read_b64_tr_b16 v[156:157], v3 offset:43008
	ds_read_b64_tr_b16 v[158:159], v3 offset:47104
	s_waitcnt lgkmcnt(2)
	v_mfma_f32_32x32x16_bf16 v[84:99], v[148:151], v[152:155], v[84:99]
	ds_read_b64_tr_b16 v[152:153], v3 offset:43520
	ds_read_b64_tr_b16 v[154:155], v3 offset:47616
	s_waitcnt lgkmcnt(2)
	v_mfma_f32_32x32x16_bf16 v[68:83], v[148:151], v[156:159], v[68:83]
	ds_read_b64_tr_b16 v[156:157], v3 offset:44032
	ds_read_b64_tr_b16 v[158:159], v3 offset:48128
	s_waitcnt lgkmcnt(2)
	v_mfma_f32_32x32x16_bf16 v[52:67], v[148:151], v[152:155], v[52:67]
	ds_read_b64_tr_b16 v[152:153], v3 offset:44544
	ds_read_b64_tr_b16 v[154:155], v3 offset:48640
	s_waitcnt lgkmcnt(2)
	v_mfma_f32_32x32x16_bf16 v[36:51], v[148:151], v[156:159], v[36:51]
	s_waitcnt lgkmcnt(0)
	v_mfma_f32_32x32x16_bf16 v[20:35], v[148:151], v[152:155], v[20:35]
	s_barrier
	s_setprio 3
	ds_read_b128 v[180:183], v225 offset:4096
	ds_read_b128 v[184:187], v226 offset:4096
	s_waitcnt lgkmcnt(1)
	v_mfma_i32_32x32x32_i8 v[148:163], v[180:183], v[164:167], v[132:147]
	ds_read_b128 v[180:183], v227 offset:4096
	s_waitcnt lgkmcnt(1)
	v_mfma_i32_32x32x32_i8 v[148:163], v[184:187], v[168:171], v[148:163]
	ds_read_b128 v[188:191], v228 offset:4096
	s_waitcnt lgkmcnt(1)
	v_mfma_i32_32x32x32_i8 v[148:163], v[180:183], v[172:175], v[148:163]
	ds_read_b64_tr_b16 v[184:185], v3 offset:49152
	ds_read_b64_tr_b16 v[186:187], v3 offset:53248
	s_waitcnt lgkmcnt(2)
	v_mfma_i32_32x32x32_i8 v[148:163], v[188:191], v[176:179], v[148:163]
	ds_read_b64_tr_b16 v[180:181], v3 offset:49664
	ds_read_b64_tr_b16 v[182:183], v3 offset:53760
	s_nop 9
	v_max3_f32 v188, v148, v149, v150
	v_max3_f32 v189, v151, v152, v153
	v_max3_f32 v190, v154, v155, v156
	v_max3_f32 v191, v157, v158, v159
	v_max3_f32 v192, v160, v161, v162
	v_max3_f32 v188, v188, v189, v190
	v_max3_f32 v191, v191, v192, v163
	v_max_f32_e32 v188, v188, v191
	v_add_f32_e32 v188, 0xcb400000, v188
	v_fma_f32 v189, v207, v188, -v237
	v_cmp_gt_f32_e32 vcc, v189, v220
	s_cbranch_vccnz .Lv2_rare_h2
.Lv2_back_h2:
	v_mul_f32_e32 v189, v221, v207
	v_fma_f32 v190, s100, v189, v255
	v_fma_f32 v148, v148, v189, -v190
	v_fma_f32 v149, v149, v189, -v190
	v_exp_f32_e32 v148, v148
	v_fma_f32 v150, v150, v189, -v190
	v_exp_f32_e32 v149, v149
	v_fma_f32 v151, v151, v189, -v190
	v_exp_f32_e32 v150, v150
	v_fma_f32 v152, v152, v189, -v190
	v_exp_f32_e32 v151, v151
	v_fma_f32 v153, v153, v189, -v190
	v_exp_f32_e32 v152, v152
	v_fma_f32 v154, v154, v189, -v190
	v_exp_f32_e32 v153, v153
	v_fma_f32 v155, v155, v189, -v190
	v_exp_f32_e32 v154, v154
	v_fma_f32 v156, v156, v189, -v190
	v_exp_f32_e32 v155, v155
	v_fma_f32 v157, v157, v189, -v190
	v_exp_f32_e32 v156, v156
	v_fma_f32 v158, v158, v189, -v190
	v_exp_f32_e32 v157, v157
	v_fma_f32 v159, v159, v189, -v190
	v_exp_f32_e32 v158, v158
	v_fma_f32 v160, v160, v189, -v190
	v_exp_f32_e32 v159, v159
	v_fma_f32 v161, v161, v189, -v190
	v_exp_f32_e32 v160, v160
	v_fma_f32 v162, v162, v189, -v190
	v_exp_f32_e32 v161, v161
	v_fma_f32 v163, v163, v189, -v190
	v_exp_f32_e32 v162, v162
	v_exp_f32_e32 v163, v163
	v_add_f32_e32 v188, v148, v149
	v_add_f32_e32 v189, v150, v151
	v_add_f32_e32 v190, v152, v153
	v_add_f32_e32 v191, v154, v155
	v_add_f32_e32 v192, v156, v157
	v_add_f32_e32 v193, v158, v159
	v_add_f32_e32 v194, v160, v161
	v_add_f32_e32 v195, v162, v163
	v_add_f32_e32 v188, v188, v189
	v_add_f32_e32 v190, v190, v191
	v_add_f32_e32 v192, v192, v193
	v_add_f32_e32 v194, v194, v195
	v_add_f32_e32 v188, v188, v190
	v_add_f32_e32 v192, v192, v194
	v_add_f32_e32 v188, v188, v192
	v_add_f32_e32 v224, v224, v188
	v_cvt_pk_bf16_f32 v155, v154, v155
	v_cvt_pk_bf16_f32 v154, v152, v153
	v_cvt_pk_bf16_f32 v152, v148, v149
	v_cvt_pk_bf16_f32 v153, v150, v151
	v_cvt_pk_bf16_f32 v148, v156, v157
	v_cvt_pk_bf16_f32 v149, v158, v159
	v_cvt_pk_bf16_f32 v150, v160, v161
	v_cvt_pk_bf16_f32 v151, v162, v163
	s_barrier
	s_setprio 0
	s_waitcnt lgkmcnt(2)
	v_mfma_f32_32x32x16_bf16 v[4:19], v[152:155], v[184:187], v[4:19]
	ds_read_b64_tr_b16 v[156:157], v3 offset:50176
	ds_read_b64_tr_b16 v[158:159], v3 offset:54272
	s_waitcnt lgkmcnt(2)
	v_mfma_f32_32x32x16_bf16 v[116:131], v[152:155], v[180:183], v[116:131]
	ds_read_b64_tr_b16 v[160:161], v3 offset:50688
	ds_read_b64_tr_b16 v[162:163], v3 offset:54784
	s_waitcnt lgkmcnt(2)
	v_mfma_f32_32x32x16_bf16 v[100:115], v[152:155], v[156:159], v[100:115]
	ds_read_b64_tr_b16 v[156:157], v3 offset:51200
	ds_read_b64_tr_b16 v[158:159], v3 offset:55296
	s_waitcnt lgkmcnt(2)
	v_mfma_f32_32x32x16_bf16 v[84:99], v[152:155], v[160:163], v[84:99]
	ds_read_b64_tr_b16 v[160:161], v3 offset:51712
	ds_read_b64_tr_b16 v[162:163], v3 offset:55808
	s_waitcnt lgkmcnt(2)
	v_mfma_f32_32x32x16_bf16 v[68:83], v[152:155], v[156:159], v[68:83]
	ds_read_b64_tr_b16 v[156:157], v3 offset:52224
	ds_read_b64_tr_b16 v[158:159], v3 offset:56320
	s_waitcnt lgkmcnt(2)
	v_mfma_f32_32x32x16_bf16 v[52:67], v[152:155], v[160:163], v[52:67]
	ds_read_b64_tr_b16 v[160:161], v3 offset:52736
	ds_read_b64_tr_b16 v[162:163], v3 offset:56832
	s_waitcnt lgkmcnt(2)
	v_mfma_f32_32x32x16_bf16 v[36:51], v[152:155], v[156:159], v[36:51]
	ds_read_b64_tr_b16 v[156:157], v3 offset:57344
	ds_read_b64_tr_b16 v[158:159], v3 offset:61440
	s_waitcnt lgkmcnt(2)
	v_mfma_f32_32x32x16_bf16 v[20:35], v[152:155], v[160:163], v[20:35]
	ds_read_b64_tr_b16 v[152:153], v3 offset:57856
	ds_read_b64_tr_b16 v[154:155], v3 offset:61952
	s_waitcnt lgkmcnt(2)
	v_mfma_f32_32x32x16_bf16 v[4:19], v[148:151], v[156:159], v[4:19]
	ds_read_b64_tr_b16 v[156:157], v3 offset:58368
	ds_read_b64_tr_b16 v[158:159], v3 offset:62464
	s_waitcnt lgkmcnt(2)
	v_mfma_f32_32x32x16_bf16 v[116:131], v[148:151], v[152:155], v[116:131]
	ds_read_b64_tr_b16 v[152:153], v3 offset:58880
	ds_read_b64_tr_b16 v[154:155], v3 offset:62976
	s_waitcnt lgkmcnt(2)
	v_mfma_f32_32x32x16_bf16 v[100:115], v[148:151], v[156:159], v[100:115]
	ds_read_b64_tr_b16 v[156:157], v3 offset:59392
	ds_read_b64_tr_b16 v[158:159], v3 offset:63488
	s_waitcnt lgkmcnt(2)
	v_mfma_f32_32x32x16_bf16 v[84:99], v[148:151], v[152:155], v[84:99]
	ds_read_b64_tr_b16 v[152:153], v3 offset:59904
	ds_read_b64_tr_b16 v[154:155], v3 offset:64000
	s_waitcnt lgkmcnt(2)
	v_mfma_f32_32x32x16_bf16 v[68:83], v[148:151], v[156:159], v[68:83]
	ds_read_b64_tr_b16 v[156:157], v3 offset:60416
	ds_read_b64_tr_b16 v[158:159], v3 offset:64512
	s_waitcnt lgkmcnt(2)
	v_mfma_f32_32x32x16_bf16 v[52:67], v[148:151], v[152:155], v[52:67]
	ds_read_b64_tr_b16 v[152:153], v3 offset:60928
	ds_read_b64_tr_b16 v[154:155], v3 offset:65024
	s_waitcnt lgkmcnt(2)
	v_mfma_f32_32x32x16_bf16 v[36:51], v[148:151], v[156:159], v[36:51]
	s_waitcnt lgkmcnt(0)
	v_mfma_f32_32x32x16_bf16 v[20:35], v[148:151], v[152:155], v[20:35]
	s_min_u32 s85, s79, s84
	s_lshl_b32 s4, s85, 6
	s_cmp_lt_u32 s85, 4
	s_cselect_b64 s[2:3], -1, 0
	s_add_i32 s88, s4, 0xffffff00
	s_and_b64 s[86:87], s[2:3], exec
	s_cselect_b32 s4, s4, s88
	s_cselect_b32 s88, s17, s73
	s_cselect_b32 s89, s16, s72
	s_lshl_b64 s[86:87], s[4:5], 7
	s_add_u32 s86, s89, s86
	s_addc_u32 s87, s88, s87
	s_lshl_b32 s88, s85, 1
	s_mov_b32 s89, s5
	s_lshl_b64 s[88:89], s[88:89], 2
	s_add_u32 s85, s18, s88
	s_addc_u32 s90, s19, s89
	s_add_u32 s88, s74, s88
	s_addc_u32 s89, s75, s89
	s_add_u32 s88, s88, 0xffffffe0
	s_addc_u32 s89, s89, -1
	s_and_b64 s[2:3], s[2:3], exec
	s_waitcnt vmcnt(0)
	v_mov_b32_e32 v236, v209
	s_cselect_b32 s3, s90, s89
	s_cselect_b32 s2, s85, s88
	s_waitcnt vmcnt(0) lgkmcnt(0)
	s_barrier
	s_setprio 3
	global_load_dwordx2 v[206:207], v201, s[2:3]
	ds_read_b128 v[180:183], v225 offset:16384
	ds_read_b128 v[184:187], v226 offset:16384
	s_cselect_b32 s85, s21, s77
	s_cselect_b32 s88, s20, s76
	s_lshl_b64 s[2:3], s[4:5], 9
	s_add_u32 s2, s88, s2
	s_addc_u32 s3, s85, s3
	s_waitcnt lgkmcnt(1)
	v_mfma_i32_32x32x32_i8 v[148:163], v[180:183], v[164:167], v[132:147]
	ds_read_b128 v[180:183], v227 offset:16384
	s_waitcnt lgkmcnt(1)
	v_mfma_i32_32x32x32_i8 v[148:163], v[184:187], v[168:171], v[148:163]
	ds_read_b128 v[188:191], v228 offset:16384
	s_waitcnt lgkmcnt(1)
	v_mfma_i32_32x32x32_i8 v[148:163], v[180:183], v[172:175], v[148:163]
	ds_read_b64_tr_b16 v[184:185], v222 offset:32768
	ds_read_b64_tr_b16 v[186:187], v222 offset:36864
	s_waitcnt lgkmcnt(2)
	v_mfma_i32_32x32x32_i8 v[148:163], v[188:191], v[176:179], v[148:163]
	ds_read_b64_tr_b16 v[180:181], v222 offset:33280
	ds_read_b64_tr_b16 v[182:183], v222 offset:37376
	s_nop 9
	s_mov_b32 s90, s94
	v_max3_f32 v188, v148, v149, v150
	v_max3_f32 v189, v151, v152, v153
	v_max3_f32 v190, v154, v155, v156
	v_max3_f32 v191, v157, v158, v159
	v_max3_f32 v192, v160, v161, v162
	v_max3_f32 v188, v188, v189, v190
	v_max3_f32 v191, v191, v192, v163
	v_max_f32_e32 v188, v188, v191
	v_add_f32_e32 v188, 0xcb400000, v188
	v_fma_f32 v189, v208, v188, -v237
	v_cmp_gt_f32_e32 vcc, v189, v220
	s_cbranch_vccnz .Lv2_rare_h3
.Lv2_back_h3:
	v_mul_f32_e32 v189, v221, v208
	v_fma_f32 v190, s100, v189, v255
	v_fma_f32 v148, v148, v189, -v190
	v_fma_f32 v149, v149, v189, -v190
	v_exp_f32_e32 v148, v148
	v_fma_f32 v150, v150, v189, -v190
	v_exp_f32_e32 v149, v149
	v_fma_f32 v151, v151, v189, -v190
	v_exp_f32_e32 v150, v150
	v_fma_f32 v152, v152, v189, -v190
	v_exp_f32_e32 v151, v151
	v_fma_f32 v153, v153, v189, -v190
	v_exp_f32_e32 v152, v152
	v_fma_f32 v154, v154, v189, -v190
	v_exp_f32_e32 v153, v153
	v_fma_f32 v155, v155, v189, -v190
	v_exp_f32_e32 v154, v154
	v_fma_f32 v156, v156, v189, -v190
	v_exp_f32_e32 v155, v155
	v_fma_f32 v157, v157, v189, -v190
	v_exp_f32_e32 v156, v156
	v_fma_f32 v158, v158, v189, -v190
	v_exp_f32_e32 v157, v157
	v_fma_f32 v159, v159, v189, -v190
	v_exp_f32_e32 v158, v158
	v_fma_f32 v160, v160, v189, -v190
	v_exp_f32_e32 v159, v159
	v_fma_f32 v161, v161, v189, -v190
	v_exp_f32_e32 v160, v160
	v_fma_f32 v162, v162, v189, -v190
	v_exp_f32_e32 v161, v161
	v_fma_f32 v163, v163, v189, -v190
	v_exp_f32_e32 v162, v162
	v_exp_f32_e32 v163, v163
	v_add_f32_e32 v188, v148, v149
	v_add_f32_e32 v189, v150, v151
	v_add_f32_e32 v190, v152, v153
	v_add_f32_e32 v191, v154, v155
	v_add_f32_e32 v192, v156, v157
	v_add_f32_e32 v193, v158, v159
	v_add_f32_e32 v194, v160, v161
	v_add_f32_e32 v195, v162, v163
	v_add_f32_e32 v188, v188, v189
	v_add_f32_e32 v190, v190, v191
	v_add_f32_e32 v192, v192, v193
	v_add_f32_e32 v194, v194, v195
	v_add_f32_e32 v188, v188, v190
	v_add_f32_e32 v192, v192, v194
	v_add_f32_e32 v188, v188, v192
	v_add_f32_e32 v224, v224, v188
	v_cvt_pk_bf16_f32 v155, v154, v155
	v_cvt_pk_bf16_f32 v154, v152, v153
	v_cvt_pk_bf16_f32 v152, v148, v149
	v_cvt_pk_bf16_f32 v153, v150, v151
	v_cvt_pk_bf16_f32 v148, v156, v157
	v_cvt_pk_bf16_f32 v149, v158, v159
	v_cvt_pk_bf16_f32 v150, v160, v161
	v_cvt_pk_bf16_f32 v151, v162, v163
	s_barrier
	s_setprio 0
	s_waitcnt lgkmcnt(2)
	v_mfma_f32_32x32x16_bf16 v[4:19], v[152:155], v[184:187], v[4:19]
	ds_read_b64_tr_b16 v[156:157], v222 offset:33792
	ds_read_b64_tr_b16 v[158:159], v222 offset:37888
	s_waitcnt lgkmcnt(2)
	v_mfma_f32_32x32x16_bf16 v[116:131], v[152:155], v[180:183], v[116:131]
	ds_read_b64_tr_b16 v[160:161], v222 offset:34304
	ds_read_b64_tr_b16 v[162:163], v222 offset:38400
	s_add_i32 m0, s83, 0
	s_nop 0
	global_load_lds_dwordx4 v200, s[86:87]
	s_waitcnt lgkmcnt(2)
	v_mfma_f32_32x32x16_bf16 v[100:115], v[152:155], v[156:159], v[100:115]
	ds_read_b64_tr_b16 v[156:157], v222 offset:34816
	ds_read_b64_tr_b16 v[158:159], v222 offset:38912
	s_waitcnt lgkmcnt(2)
	v_mfma_f32_32x32x16_bf16 v[84:99], v[152:155], v[160:163], v[84:99]
	ds_read_b64_tr_b16 v[160:161], v222 offset:35328
	ds_read_b64_tr_b16 v[162:163], v222 offset:39424
	s_add_i32 m0, s82, 0
	s_nop 0
	global_load_lds_dwordx4 v204, s[2:3]
	s_waitcnt lgkmcnt(2)
	v_mfma_f32_32x32x16_bf16 v[68:83], v[152:155], v[156:159], v[68:83]
	ds_read_b64_tr_b16 v[156:157], v222 offset:35840
	ds_read_b64_tr_b16 v[158:159], v222 offset:39936
	s_waitcnt lgkmcnt(2)
	v_mfma_f32_32x32x16_bf16 v[52:67], v[152:155], v[160:163], v[52:67]
	ds_read_b64_tr_b16 v[160:161], v222 offset:36352
	ds_read_b64_tr_b16 v[162:163], v222 offset:40448
	s_add_u32 s2, s2, 0x80
	s_addc_u32 s3, s3, 0
	s_add_i32 m0, s82, 0x400
	s_nop 0
	global_load_lds_dwordx4 v204, s[2:3]
	s_waitcnt lgkmcnt(2)
	v_mfma_f32_32x32x16_bf16 v[36:51], v[152:155], v[156:159], v[36:51]
	ds_read_b64_tr_b16 v[156:157], v222 offset:40960
	ds_read_b64_tr_b16 v[158:159], v222 offset:45056
	s_waitcnt lgkmcnt(2)
	v_mfma_f32_32x32x16_bf16 v[20:35], v[152:155], v[160:163], v[20:35]
	ds_read_b64_tr_b16 v[152:153], v222 offset:41472
	ds_read_b64_tr_b16 v[154:155], v222 offset:45568
	s_add_u32 s2, s2, 0x80
	s_addc_u32 s3, s3, 0
	s_add_i32 m0, s82, 0x800
	s_nop 0
	global_load_lds_dwordx4 v204, s[2:3]
	s_waitcnt lgkmcnt(2)
	v_mfma_f32_32x32x16_bf16 v[4:19], v[148:151], v[156:159], v[4:19]
	ds_read_b64_tr_b16 v[156:157], v222 offset:41984
	ds_read_b64_tr_b16 v[158:159], v222 offset:46080
	s_waitcnt lgkmcnt(2)
	v_mfma_f32_32x32x16_bf16 v[116:131], v[148:151], v[152:155], v[116:131]
	ds_read_b64_tr_b16 v[152:153], v222 offset:42496
	ds_read_b64_tr_b16 v[154:155], v222 offset:46592
	s_add_u32 s2, s2, 0x80
	s_addc_u32 s3, s3, 0
	s_add_i32 m0, s82, 0xc00
	s_nop 0
	global_load_lds_dwordx4 v204, s[2:3]
	s_waitcnt lgkmcnt(2)
	v_mfma_f32_32x32x16_bf16 v[100:115], v[148:151], v[156:159], v[100:115]
	ds_read_b64_tr_b16 v[156:157], v222 offset:43008
	ds_read_b64_tr_b16 v[158:159], v222 offset:47104
	s_waitcnt lgkmcnt(2)
	v_mfma_f32_32x32x16_bf16 v[84:99], v[148:151], v[152:155], v[84:99]
	ds_read_b64_tr_b16 v[152:153], v222 offset:43520
	ds_read_b64_tr_b16 v[154:155], v222 offset:47616
	s_waitcnt lgkmcnt(2)
	v_mfma_f32_32x32x16_bf16 v[68:83], v[148:151], v[156:159], v[68:83]
	ds_read_b64_tr_b16 v[156:157], v222 offset:44032
	ds_read_b64_tr_b16 v[158:159], v222 offset:48128
	s_waitcnt lgkmcnt(2)
	v_mfma_f32_32x32x16_bf16 v[52:67], v[148:151], v[152:155], v[52:67]
	ds_read_b64_tr_b16 v[152:153], v222 offset:44544
	ds_read_b64_tr_b16 v[154:155], v222 offset:48640
	s_waitcnt lgkmcnt(2)
	v_mfma_f32_32x32x16_bf16 v[36:51], v[148:151], v[156:159], v[36:51]
	s_waitcnt lgkmcnt(0)
	v_mfma_f32_32x32x16_bf16 v[20:35], v[148:151], v[152:155], v[20:35]
	s_barrier
	s_setprio 3
	ds_read_b128 v[180:183], v225 offset:20480
	ds_read_b128 v[184:187], v226 offset:20480
	s_waitcnt lgkmcnt(1)
	v_mfma_i32_32x32x32_i8 v[148:163], v[180:183], v[164:167], v[132:147]
	ds_read_b128 v[180:183], v227 offset:20480
	s_waitcnt lgkmcnt(1)
	v_mfma_i32_32x32x32_i8 v[148:163], v[184:187], v[168:171], v[148:163]
	ds_read_b128 v[188:191], v228 offset:20480
	s_waitcnt lgkmcnt(1)
	v_mfma_i32_32x32x32_i8 v[148:163], v[180:183], v[172:175], v[148:163]
	ds_read_b64_tr_b16 v[184:185], v222 offset:49152
	ds_read_b64_tr_b16 v[186:187], v222 offset:53248
	s_waitcnt lgkmcnt(2)
	v_mfma_i32_32x32x32_i8 v[148:163], v[188:191], v[176:179], v[148:163]
	ds_read_b64_tr_b16 v[180:181], v222 offset:49664
	ds_read_b64_tr_b16 v[182:183], v222 offset:53760
	s_nop 9
	v_max3_f32 v188, v148, v149, v150
	v_max3_f32 v189, v151, v152, v153
	v_max3_f32 v190, v154, v155, v156
	v_max3_f32 v191, v157, v158, v159
	v_max3_f32 v192, v160, v161, v162
	v_max3_f32 v188, v188, v189, v190
	v_max3_f32 v191, v191, v192, v163
	v_max_f32_e32 v188, v188, v191
	v_add_f32_e32 v188, 0xcb400000, v188
	v_fma_f32 v189, v236, v188, -v237
	v_cmp_gt_f32_e32 vcc, v189, v220
	s_cbranch_vccnz .Lv2_rare_h4

.Lb4_mid:
	s_barrier
	s_setprio 3
	s_waitcnt vmcnt(0)
	global_load_dwordx2 v[208:209], v201, s[2:3]
	s_cselect_b32 s85, s21, s77
	s_cselect_b32 s88, s20, s76
	s_lshl_b64 s[2:3], s[4:5], 9
	s_add_u32 s2, s88, s2
	ds_read_b128 v[180:183], v225
	ds_read_b128 v[184:187], v226
	s_addc_u32 s3, s85, s3
	s_cmp_lg_u32 0, -1
	s_cselect_b32 s4, 0, 0
	s_add_i32 s85, s4, s80
	s_add_i32 s4, s4, s81
	s_addk_i32 s85, 0x4000
	s_add_i32 s88, s4, 0x10000
	s_waitcnt lgkmcnt(1)
	v_mfma_i32_32x32x32_i8 v[148:163], v[180:183], v[164:167], v[132:147]
	ds_read_b128 v[180:183], v227
	s_waitcnt lgkmcnt(1)
	v_mfma_i32_32x32x32_i8 v[148:163], v[184:187], v[168:171], v[148:163]
	ds_read_b128 v[188:191], v228
	s_waitcnt lgkmcnt(1)
	v_mfma_i32_32x32x32_i8 v[148:163], v[180:183], v[172:175], v[148:163]
	ds_read_b64_tr_b16 v[184:185], v3 offset:32768
	ds_read_b64_tr_b16 v[186:187], v3 offset:36864
	s_waitcnt lgkmcnt(2)
	v_mfma_i32_32x32x32_i8 v[148:163], v[188:191], v[176:179], v[148:163]
	ds_read_b64_tr_b16 v[180:181], v3 offset:33280
	ds_read_b64_tr_b16 v[182:183], v3 offset:37376
	s_nop 9
	v_max3_f32 v188, v148, v149, v150
	v_max3_f32 v189, v151, v152, v153
	v_max3_f32 v190, v154, v155, v156
	v_max3_f32 v191, v157, v158, v159
	v_max3_f32 v192, v160, v161, v162
	v_max3_f32 v188, v188, v189, v190
	v_max3_f32 v191, v191, v192, v163
	v_max_f32_e32 v188, v188, v191
	v_add_f32_e32 v188, 0xcb400000, v188
	v_fma_f32 v189, v206, v188, -v237
	v_cmp_gt_f32_e32 vcc, v189, v220
	s_cbranch_vccnz .Lb2_rare_h1

.Lb2_back_h2:
	v_mul_f32_e32 v189, v221, v207
	v_fma_f32 v190, s100, v189, v255
	v_fma_f32 v148, v148, v189, -v190
	v_fma_f32 v149, v149, v189, -v190
	v_exp_f32_e32 v148, v148
	v_fma_f32 v150, v150, v189, -v190
	v_exp_f32_e32 v149, v149
	v_fma_f32 v151, v151, v189, -v190
	v_exp_f32_e32 v150, v150
	v_fma_f32 v152, v152, v189, -v190
	v_exp_f32_e32 v151, v151
	v_fma_f32 v153, v153, v189, -v190
	v_exp_f32_e32 v152, v152
	v_fma_f32 v154, v154, v189, -v190
	v_exp_f32_e32 v153, v153
	v_fma_f32 v155, v155, v189, -v190
	v_exp_f32_e32 v154, v154
	v_fma_f32 v156, v156, v189, -v190
	v_exp_f32_e32 v155, v155
	v_fma_f32 v157, v157, v189, -v190
	v_exp_f32_e32 v156, v156
	v_fma_f32 v158, v158, v189, -v190
	v_exp_f32_e32 v157, v157
	v_fma_f32 v159, v159, v189, -v190
	v_exp_f32_e32 v158, v158
	v_fma_f32 v160, v160, v189, -v190
	v_exp_f32_e32 v159, v159
	v_fma_f32 v161, v161, v189, -v190
	v_exp_f32_e32 v160, v160
	v_fma_f32 v162, v162, v189, -v190
	v_exp_f32_e32 v161, v161
	v_fma_f32 v163, v163, v189, -v190
	v_exp_f32_e32 v162, v162
	v_exp_f32_e32 v163, v163
	v_add_f32_e32 v188, v148, v149
	v_add_f32_e32 v189, v150, v151
	v_add_f32_e32 v190, v152, v153
	v_add_f32_e32 v191, v154, v155
	v_add_f32_e32 v192, v156, v157
	v_add_f32_e32 v193, v158, v159
	v_add_f32_e32 v194, v160, v161
	v_add_f32_e32 v195, v162, v163
	v_add_f32_e32 v188, v188, v189
	v_add_f32_e32 v190, v190, v191
	v_add_f32_e32 v192, v192, v193
	v_add_f32_e32 v194, v194, v195
	v_add_f32_e32 v188, v188, v190
	v_add_f32_e32 v192, v192, v194
	v_add_f32_e32 v188, v188, v192
	v_add_f32_e32 v224, v224, v188
	v_cvt_pk_bf16_f32 v155, v154, v155
	v_cvt_pk_bf16_f32 v154, v152, v153
	v_cvt_pk_bf16_f32 v152, v148, v149
	v_cvt_pk_bf16_f32 v153, v150, v151
	v_cvt_pk_bf16_f32 v148, v156, v157
	v_cvt_pk_bf16_f32 v149, v158, v159
	v_cvt_pk_bf16_f32 v150, v160, v161
	v_cvt_pk_bf16_f32 v151, v162, v163
	s_min_u32 s85, s79, s84
	s_lshl_b32 s4, s85, 6
	s_cmp_lt_u32 s85, 4
	s_cselect_b64 s[2:3], -1, 0
	s_add_i32 s88, s4, 0xffffff00
	s_and_b64 s[86:87], s[2:3], exec
	s_cselect_b32 s4, s4, s88
	s_cselect_b32 s88, s17, s73
	s_cselect_b32 s89, s16, s72
	s_lshl_b64 s[86:87], s[4:5], 7
	s_add_u32 s86, s89, s86
	s_addc_u32 s87, s88, s87
	s_lshl_b32 s88, s85, 1
	s_mov_b32 s89, s5
	s_lshl_b64 s[88:89], s[88:89], 2
	s_add_u32 s85, s18, s88
	s_addc_u32 s90, s19, s89
	s_add_u32 s88, s74, s88
	s_addc_u32 s89, s75, s89
	s_add_u32 s88, s88, 0xffffffe0
	s_addc_u32 s89, s89, -1
	s_and_b64 s[2:3], s[2:3], exec
	s_waitcnt vmcnt(0)
	v_mov_b32_e32 v236, v209
	s_cselect_b32 s3, s90, s89
	s_cselect_b32 s2, s85, s88
	s_waitcnt vmcnt(0) lgkmcnt(0)
	s_barrier
	s_setprio 0
	s_waitcnt lgkmcnt(2)
	v_mfma_f32_32x32x16_bf16 v[4:19], v[152:155], v[184:187], v[4:19]
	ds_read_b64_tr_b16 v[156:157], v3 offset:50176
	ds_read_b64_tr_b16 v[158:159], v3 offset:54272
	s_waitcnt lgkmcnt(2)
	v_mfma_f32_32x32x16_bf16 v[116:131], v[152:155], v[180:183], v[116:131]
	ds_read_b64_tr_b16 v[160:161], v3 offset:50688
	ds_read_b64_tr_b16 v[162:163], v3 offset:54784
	s_waitcnt lgkmcnt(2)
	v_mfma_f32_32x32x16_bf16 v[100:115], v[152:155], v[156:159], v[100:115]
	ds_read_b64_tr_b16 v[156:157], v3 offset:51200
	ds_read_b64_tr_b16 v[158:159], v3 offset:55296
	s_waitcnt lgkmcnt(2)
	v_mfma_f32_32x32x16_bf16 v[84:99], v[152:155], v[160:163], v[84:99]
	ds_read_b64_tr_b16 v[160:161], v3 offset:51712
	ds_read_b64_tr_b16 v[162:163], v3 offset:55808
	s_waitcnt lgkmcnt(2)
	v_mfma_f32_32x32x16_bf16 v[68:83], v[152:155], v[156:159], v[68:83]
	ds_read_b64_tr_b16 v[156:157], v3 offset:52224
	ds_read_b64_tr_b16 v[158:159], v3 offset:56320
	s_waitcnt lgkmcnt(2)
	v_mfma_f32_32x32x16_bf16 v[52:67], v[152:155], v[160:163], v[52:67]
	ds_read_b64_tr_b16 v[160:161], v3 offset:52736
	ds_read_b64_tr_b16 v[162:163], v3 offset:56832
	s_waitcnt lgkmcnt(2)
	v_mfma_f32_32x32x16_bf16 v[36:51], v[152:155], v[156:159], v[36:51]
	ds_read_b64_tr_b16 v[156:157], v3 offset:57344
	ds_read_b64_tr_b16 v[158:159], v3 offset:61440
	s_waitcnt lgkmcnt(2)
	v_mfma_f32_32x32x16_bf16 v[20:35], v[152:155], v[160:163], v[20:35]
	ds_read_b64_tr_b16 v[152:153], v3 offset:57856
	ds_read_b64_tr_b16 v[154:155], v3 offset:61952
	s_waitcnt lgkmcnt(2)
	v_mfma_f32_32x32x16_bf16 v[4:19], v[148:151], v[156:159], v[4:19]
	ds_read_b64_tr_b16 v[156:157], v3 offset:58368
	ds_read_b64_tr_b16 v[158:159], v3 offset:62464
	s_waitcnt lgkmcnt(2)
	v_mfma_f32_32x32x16_bf16 v[116:131], v[148:151], v[152:155], v[116:131]
	ds_read_b64_tr_b16 v[152:153], v3 offset:58880
	ds_read_b64_tr_b16 v[154:155], v3 offset:62976
	s_waitcnt lgkmcnt(2)
	v_mfma_f32_32x32x16_bf16 v[100:115], v[148:151], v[156:159], v[100:115]
	ds_read_b64_tr_b16 v[156:157], v3 offset:59392
	ds_read_b64_tr_b16 v[158:159], v3 offset:63488
	s_waitcnt lgkmcnt(2)
	v_mfma_f32_32x32x16_bf16 v[84:99], v[148:151], v[152:155], v[84:99]
	ds_read_b64_tr_b16 v[152:153], v3 offset:59904
	ds_read_b64_tr_b16 v[154:155], v3 offset:64000
	s_waitcnt lgkmcnt(2)
	v_mfma_f32_32x32x16_bf16 v[68:83], v[148:151], v[156:159], v[68:83]
	ds_read_b64_tr_b16 v[156:157], v3 offset:60416
	ds_read_b64_tr_b16 v[158:159], v3 offset:64512
	s_waitcnt lgkmcnt(2)
	v_mfma_f32_32x32x16_bf16 v[52:67], v[148:151], v[152:155], v[52:67]
	ds_read_b64_tr_b16 v[152:153], v3 offset:60928
	ds_read_b64_tr_b16 v[154:155], v3 offset:65024
	s_waitcnt lgkmcnt(2)
	v_mfma_f32_32x32x16_bf16 v[36:51], v[148:151], v[156:159], v[36:51]
	s_waitcnt lgkmcnt(0)
	v_mfma_f32_32x32x16_bf16 v[20:35], v[148:151], v[152:155], v[20:35]
	s_barrier
	s_setprio 3
	global_load_dwordx2 v[206:207], v201, s[2:3]
	ds_read_b128 v[180:183], v225 offset:16384
	ds_read_b128 v[184:187], v226 offset:16384
	s_cselect_b32 s85, s21, s77
	s_cselect_b32 s88, s20, s76
	s_lshl_b64 s[2:3], s[4:5], 9
	s_add_u32 s2, s88, s2
	s_addc_u32 s3, s85, s3
	s_waitcnt lgkmcnt(1)
	v_mfma_i32_32x32x32_i8 v[148:163], v[180:183], v[164:167], v[132:147]
	ds_read_b128 v[180:183], v227 offset:16384
	s_waitcnt lgkmcnt(1)
	v_mfma_i32_32x32x32_i8 v[148:163], v[184:187], v[168:171], v[148:163]
	ds_read_b128 v[188:191], v228 offset:16384
	s_waitcnt lgkmcnt(1)
	v_mfma_i32_32x32x32_i8 v[148:163], v[180:183], v[172:175], v[148:163]
	ds_read_b64_tr_b16 v[184:185], v222 offset:32768
	ds_read_b64_tr_b16 v[186:187], v222 offset:36864
	s_waitcnt lgkmcnt(2)
	v_mfma_i32_32x32x32_i8 v[148:163], v[188:191], v[176:179], v[148:163]
	ds_read_b64_tr_b16 v[180:181], v222 offset:33280
	ds_read_b64_tr_b16 v[182:183], v222 offset:37376
	s_nop 9
	s_mov_b32 s90, s94
	v_max3_f32 v188, v148, v149, v150
	v_max3_f32 v189, v151, v152, v153
	v_max3_f32 v190, v154, v155, v156
	v_max3_f32 v191, v157, v158, v159
	v_max3_f32 v192, v160, v161, v162
	v_max3_f32 v188, v188, v189, v190
	v_max3_f32 v191, v191, v192, v163
	v_max_f32_e32 v188, v188, v191
	v_add_f32_e32 v188, 0xcb400000, v188
	v_fma_f32 v189, v208, v188, -v237
	v_cmp_gt_f32_e32 vcc, v189, v220
	s_cbranch_vccnz .Lb2_rare_h3
